# prompt attention unit: the two branch folds (after the selected stream, and the final fold to bf16) issue their gate and accumulator loads together and wait with counts instead of ten dependent round
# baseline (speedup 1.0000x reference)
; #define LAS __attribute__((address_space(3)))
; template <class Tp> DEV Tp* wsp(const Frame& F, size_t off) { return (Tp*)(F.ws + off); }
; #define RESET_STATE() do { _Pragma("unroll") for (int g = 0; g < 2; ++g) { m[g] = NEG_INF; L[g] = (f32x4){0.f, 0.f, 0.f, 0.f}; _Pragma("unroll") for (int dt = 0; dt < 4; ++dt) O[g][dt] = (f32x4){0.f, 0.f, 0.f, 0.f}; } } while (0)
; #define FOLD_BRANCH(br) do { _Pragma("unroll") for (int g = 0; g < 2; ++g) { const float lt = __shfl(L[g][0], C.n); \
;         const float gsc = (lt > 0.f) ? GA[(size_t)C.tq[g] * 24 + (kv * 4 + C.h) * 3 + (br)] / lt : 0.f; _Pragma("unroll") for (int dt = 0; dt < 4; ++dt) { f32x4* ap_ = (f32x4*)ACC_AT(g, dt); *ap_ = *ap_ + O[g][dt] * gsc; } } } while (0)
; DEV void attn_unit_mfma(Frame& F, int qg, int kv) {
;     ...
;     FOLD_BRANCH(1);
;     const int iw0 = (t0 >= 512) ? 0 : (512 - t0) >> 6;
;     RESET_STATE();
;     for (int rep_ = 0; rep_ < ((PROBE_REP >> 17) & 1) + 1; ++rep_) { RESET_STATE();
;     stream_tiles_dma<DMA_SLOTS_W, true>(F, 9 - iw0, wsp<bf16>(F, WS_KW) + kv * 64, wsp<bf16>(F, WS_VW) + kv * 64, [&](int i) { return t0 - 512 + 64 * (i + iw0); }, [&](int i, const LAS unsigned char* Kb, const LAS unsigned char* Vb) {
.LBB0_1258:
	ds_bpermute_b32 v1, v178, v58
	ds_bpermute_b32 v100, v178, v42
	global_load_dword v98, v[154:155], off offset:4
	global_load_dword v99, v[148:149], off offset:4
	global_load_dwordx4 v[66:69], v[152:153], off
	global_load_dwordx4 v[70:73], v[152:153], off offset:64
	global_load_dwordx4 v[74:77], v[152:153], off offset:128
	global_load_dwordx4 v[78:81], v[152:153], off offset:192
	global_load_dwordx4 v[82:85], v[150:151], off
	global_load_dwordx4 v[86:89], v[150:151], off offset:64
	global_load_dwordx4 v[90:93], v[150:151], off offset:128
	global_load_dwordx4 v[94:97], v[150:151], off offset:192
	v_mov_b32_e32 v44, 0
	v_mov_b32_e32 v58, 0
	s_waitcnt lgkmcnt(0)
	v_cmp_lt_f32_e32 vcc, 0, v1
	s_and_saveexec_b64 s[8:9], vcc
	s_cbranch_execz .Lmy_fold1_g0
	s_waitcnt vmcnt(9)
	v_div_scale_f32 v45, s[10:11], v1, v1, v98
	v_rcp_f32_e32 v58, v45
	v_div_scale_f32 v59, vcc, v98, v1, v98
	v_fma_f32 v60, -v45, v58, 1.0
	v_fmac_f32_e32 v58, v60, v58
	v_mul_f32_e32 v60, v59, v58
	v_fma_f32 v61, -v45, v60, v59
	v_fmac_f32_e32 v60, v61, v58
	v_fma_f32 v45, -v45, v60, v59
	v_div_fmas_f32 v45, v45, v58, v60
	v_div_fixup_f32 v58, v45, v1, v98
.Lmy_fold1_g0:
	s_or_b64 exec, exec, s[8:9]
	v_cmp_lt_f32_e32 vcc, 0, v100
	s_and_saveexec_b64 s[8:9], vcc
	s_cbranch_execz .Lmy_fold1_g1
	s_waitcnt vmcnt(8)
	v_div_scale_f32 v43, s[10:11], v100, v100, v99
	v_rcp_f32_e32 v44, v43
	v_div_scale_f32 v101, vcc, v99, v100, v99
	v_fma_f32 v102, -v43, v44, 1.0
	v_fmac_f32_e32 v44, v102, v44
	v_mul_f32_e32 v102, v101, v44
	v_fma_f32 v103, -v43, v102, v101
	v_fmac_f32_e32 v102, v103, v44
	v_fma_f32 v43, -v43, v102, v101
	v_div_fmas_f32 v43, v43, v44, v102
	v_div_fixup_f32 v44, v43, v100, v99
.Lmy_fold1_g1:
	s_or_b64 exec, exec, s[8:9]
	s_waitcnt vmcnt(4)
	v_pk_fma_f32 v[64:65], v[64:65], v[58:59], v[68:69] op_sel_hi:[1,0,1]
	v_pk_fma_f32 v[62:63], v[62:63], v[58:59], v[66:67] op_sel_hi:[1,0,1]
	global_store_dwordx4 v[152:153], v[62:65], off
	v_pk_fma_f32 v[56:57], v[56:57], v[58:59], v[72:73] op_sel_hi:[1,0,1]
	v_pk_fma_f32 v[54:55], v[54:55], v[58:59], v[70:71] op_sel_hi:[1,0,1]
	global_store_dwordx4 v[152:153], v[54:57], off offset:64
	v_pk_fma_f32 v[52:53], v[52:53], v[58:59], v[76:77] op_sel_hi:[1,0,1]
	v_pk_fma_f32 v[50:51], v[50:51], v[58:59], v[74:75] op_sel_hi:[1,0,1]
	global_store_dwordx4 v[152:153], v[50:53], off offset:128
	v_pk_fma_f32 v[48:49], v[48:49], v[58:59], v[80:81] op_sel_hi:[1,0,1]
	v_pk_fma_f32 v[46:47], v[46:47], v[58:59], v[78:79] op_sel_hi:[1,0,1]
	global_store_dwordx4 v[152:153], v[46:49], off offset:192
	s_waitcnt vmcnt(4)
	v_pk_fma_f32 v[40:41], v[40:41], v[44:45], v[84:85] op_sel_hi:[1,0,1]
	v_pk_fma_f32 v[38:39], v[38:39], v[44:45], v[82:83] op_sel_hi:[1,0,1]
	global_store_dwordx4 v[150:151], v[38:41], off
	v_pk_fma_f32 v[36:37], v[36:37], v[44:45], v[88:89] op_sel_hi:[1,0,1]
	v_pk_fma_f32 v[34:35], v[34:35], v[44:45], v[86:87] op_sel_hi:[1,0,1]
	global_store_dwordx4 v[150:151], v[34:37], off offset:64
	v_pk_fma_f32 v[32:33], v[32:33], v[44:45], v[92:93] op_sel_hi:[1,0,1]
	v_pk_fma_f32 v[30:31], v[30:31], v[44:45], v[90:91] op_sel_hi:[1,0,1]
	global_store_dwordx4 v[150:151], v[30:33], off offset:128
	v_pk_fma_f32 v[28:29], v[28:29], v[44:45], v[96:97] op_sel_hi:[1,0,1]
	v_pk_fma_f32 v[26:27], v[26:27], v[44:45], v[94:95] op_sel_hi:[1,0,1]
	global_store_dwordx4 v[150:151], v[26:29], off offset:192
	s_sub_i32 s8, 0x200, s20
	s_ashr_i32 s8, s8, 6
	s_cmpk_gt_u32 s78, 0x117
	v_mov_b32_e32 v1, v138
	s_cselect_b32 s38, s8, 0
	s_lshl_b32 s24, s38, 6
	s_sub_i32 s39, 9, s38
	s_sub_i32 s25, s24, s21
	s_min_u32 s10, s39, 5
	v_mov_b32_e32 v131, v19
	s_add_i32 s8, s25, 0x45c0
	s_mov_b32 s11, s51
	s_nop 1
	v_ashrrev_i32_e32 v26, 3, v1
	v_xor_b32_e32 v1, v26, v1
	v_lshlrev_b32_e32 v27, 8, v26
	v_lshlrev_b32_e32 v1, 4, v1
	v_and_or_b32 v130, v1, s84, v27

; DEV unsigned cvtpk(float lo, float hi) { typedef float f2 __attribute__((ext_vector_type(2))); typedef __bf16 b2 __attribute__((ext_vector_type(2))); f2 v = {lo, hi}; b2 b = __builtin_convertvector(v, b2); return __builtin_bit_cast(unsigned, b); }
; template <class Tp> DEV Tp* wsp(const Frame& F, size_t off) { return (Tp*)(F.ws + off); }
; DEV void attn_unit_mfma(Frame& F, int qg, int kv) {
;     ...
;     bf16* OA = wsp<bf16>(F, WS_OA);
; #pragma unroll
;     for (int g = 0; g < 2; ++g) { const float lt = __shfl(L[g][0], C.n); const float gsc = (lt > 0.f) ? GA[(size_t)C.tq[g] * 24 + (kv * 4 + C.h) * 3 + 2] / lt : 0.f;
; #pragma unroll
;         for (int dt = 0; dt < 4; ++dt) { const f32x4 o = *(const f32x4*)ACC_AT(g, dt) + O[g][dt] * gsc; v2u wv; wv.x = cvtpk(o[0], o[1]); wv.y = cvtpk(o[2], o[3]); *(v2u*)(OA + (size_t)C.tq[g] * 512 + (kv * 4 + C.h) * 64 + 16 * dt + 4 * C.q4) = wv; } }
;     ...
;     __syncthreads();
.LBB0_1299:
	s_nop 5
	ds_bpermute_b32 v1, v178, v62
	ds_bpermute_b32 v238, v178, v42
	s_barrier
	global_load_dword v236, v[154:155], off offset:8
	global_load_dword v237, v[148:149], off offset:8
	global_load_dwordx4 v[180:183], v[152:153], off
	global_load_dwordx4 v[184:187], v[152:153], off offset:64
	global_load_dwordx4 v[188:191], v[152:153], off offset:128
	global_load_dwordx4 v[192:195], v[152:153], off offset:192
	global_load_dwordx4 v[196:199], v[150:151], off
	global_load_dwordx4 v[200:203], v[150:151], off offset:64
	global_load_dwordx4 v[228:231], v[150:151], off offset:128
	global_load_dwordx4 v[232:235], v[150:151], off offset:192
	v_mov_b32_e32 v2, 0
	v_mov_b32_e32 v6, 0
	s_waitcnt lgkmcnt(0)
	v_cmp_lt_f32_e32 vcc, 0, v1
	s_and_saveexec_b64 s[8:9], vcc
	s_cbranch_execz .Lmy_ff_g0
	s_waitcnt vmcnt(9)
	v_div_scale_f32 v4, s[10:11], v1, v1, v236
	v_rcp_f32_e32 v6, v4
	v_div_scale_f32 v5, vcc, v236, v1, v236
	v_fma_f32 v7, -v4, v6, 1.0
	v_fmac_f32_e32 v6, v7, v6
	v_mul_f32_e32 v7, v5, v6
	v_fma_f32 v8, -v4, v7, v5
	v_fmac_f32_e32 v7, v8, v6
	v_fma_f32 v4, -v4, v7, v5
	v_div_fmas_f32 v4, v4, v6, v7
	v_div_fixup_f32 v6, v4, v1, v236
.Lmy_ff_g0:
	s_or_b64 exec, exec, s[8:9]
	v_cmp_lt_f32_e32 vcc, 0, v238
	s_and_saveexec_b64 s[8:9], vcc
	s_cbranch_execz .Lmy_ff_g1
	s_waitcnt vmcnt(8)
	v_div_scale_f32 v3, s[10:11], v238, v238, v237
	v_rcp_f32_e32 v2, v3
	v_div_scale_f32 v9, vcc, v237, v238, v237
	v_fma_f32 v10, -v3, v2, 1.0
	v_fmac_f32_e32 v2, v10, v2
	v_mul_f32_e32 v10, v9, v2
	v_fma_f32 v11, -v3, v10, v9
	v_fmac_f32_e32 v10, v11, v2
	v_fma_f32 v3, -v3, v10, v9
	v_div_fmas_f32 v3, v3, v2, v10
	v_div_fixup_f32 v2, v3, v238, v237
.Lmy_ff_g1:
	s_or_b64 exec, exec, s[8:9]
	v_readlane_b32 s8, v250, 61
	v_readlane_b32 s9, v250, 62
	v_lshlrev_b32_e32 v18, 1, v18
	s_nop 1
	v_lshl_add_u64 v[4:5], s[8:9], 0, v[18:19]
	v_lshl_add_u64 v[4:5], v[20:21], 1, v[4:5]
	v_lshl_add_u64 v[12:13], v[4:5], 0, v[142:143]
	v_lshl_add_u64 v[10:11], v[4:5], 0, v[140:141]
	s_mov_b64 s[8:9], 0
	s_waitcnt vmcnt(7)
	v_pk_fma_f32 v[182:183], v[60:61], v[6:7], v[182:183] op_sel_hi:[1,0,1]
	v_pk_fma_f32 v[180:181], v[58:59], v[6:7], v[180:181] op_sel_hi:[1,0,1]
	s_nop 0
	v_cvt_pk_bf16_f32 v180, v180, v181
	v_cvt_pk_bf16_f32 v181, v182, v183
	global_store_dwordx2 v[12:13], v[180:181], off
	s_waitcnt vmcnt(7)
	v_pk_fma_f32 v[186:187], v[56:57], v[6:7], v[186:187] op_sel_hi:[1,0,1]
	v_pk_fma_f32 v[184:185], v[54:55], v[6:7], v[184:185] op_sel_hi:[1,0,1]
	s_nop 0
	v_cvt_pk_bf16_f32 v184, v184, v185
	v_cvt_pk_bf16_f32 v185, v186, v187
	global_store_dwordx2 v[12:13], v[184:185], off offset:32
	s_waitcnt vmcnt(7)
	v_pk_fma_f32 v[190:191], v[52:53], v[6:7], v[190:191] op_sel_hi:[1,0,1]
	v_pk_fma_f32 v[188:189], v[50:51], v[6:7], v[188:189] op_sel_hi:[1,0,1]
	s_nop 0
	v_cvt_pk_bf16_f32 v188, v188, v189
	v_cvt_pk_bf16_f32 v189, v190, v191
	global_store_dwordx2 v[12:13], v[188:189], off offset:64
	s_waitcnt vmcnt(7)
	v_pk_fma_f32 v[194:195], v[48:49], v[6:7], v[194:195] op_sel_hi:[1,0,1]
	v_pk_fma_f32 v[192:193], v[46:47], v[6:7], v[192:193] op_sel_hi:[1,0,1]
	s_nop 0
	v_cvt_pk_bf16_f32 v192, v192, v193
	v_cvt_pk_bf16_f32 v193, v194, v195
	global_store_dwordx2 v[12:13], v[192:193], off offset:96
	s_waitcnt vmcnt(7)
	v_pk_fma_f32 v[198:199], v[40:41], v[2:3], v[198:199] op_sel_hi:[1,0,1]
	v_pk_fma_f32 v[196:197], v[38:39], v[2:3], v[196:197] op_sel_hi:[1,0,1]
	s_nop 0
	v_cvt_pk_bf16_f32 v196, v196, v197
	v_cvt_pk_bf16_f32 v197, v198, v199
	global_store_dwordx2 v[10:11], v[196:197], off
	s_waitcnt vmcnt(7)
	v_pk_fma_f32 v[202:203], v[36:37], v[2:3], v[202:203] op_sel_hi:[1,0,1]
	v_pk_fma_f32 v[200:201], v[34:35], v[2:3], v[200:201] op_sel_hi:[1,0,1]
	s_nop 0
	v_cvt_pk_bf16_f32 v200, v200, v201
	v_cvt_pk_bf16_f32 v201, v202, v203
	global_store_dwordx2 v[10:11], v[200:201], off offset:32
	s_waitcnt vmcnt(7)
	v_pk_fma_f32 v[230:231], v[32:33], v[2:3], v[230:231] op_sel_hi:[1,0,1]
	v_pk_fma_f32 v[228:229], v[30:31], v[2:3], v[228:229] op_sel_hi:[1,0,1]
	s_nop 0
	v_cvt_pk_bf16_f32 v228, v228, v229
	v_cvt_pk_bf16_f32 v229, v230, v231
	global_store_dwordx2 v[10:11], v[228:229], off offset:64
	s_waitcnt vmcnt(7)
	v_pk_fma_f32 v[234:235], v[28:29], v[2:3], v[234:235] op_sel_hi:[1,0,1]
	v_pk_fma_f32 v[232:233], v[26:27], v[2:3], v[232:233] op_sel_hi:[1,0,1]
	s_nop 0
	v_cvt_pk_bf16_f32 v232, v232, v233
	v_cvt_pk_bf16_f32 v233, v234, v235
	global_store_dwordx2 v[10:11], v[232:233], off offset:96
	s_barrier
